# same as previous plus grid-size guards: every restructuring falls back to the baseline behaviour unless the grid is 256 workgroups
# baseline (speedup 1.0000x reference)
; #define LAS __attribute__((address_space(3)))
; __device__ __forceinline__ void p0_phase(const Args& a, LAS unsigned char* lds, int bid, int G) {
;     unsigned char* ws = a.ws;
;     const int tid = threadIdx.x, lane = tid & 63, wid = tid >> 6;
;     for (int cgp = bid; cgp < 96; cgp += G) {
;         LAS float* red = (LAS float*)lds;
;         const float* c = a.in[1]; const float* w = a.in[3]; const int n = cgp * 64 + lane;
;         float acc[8];
; #pragma unroll
;         for (int b = 0; b < 8; ++b) acc[b] = 0.f;
;         for (int k = wid * 128; k < wid * 128 + 128; ++k) { const float wv = w[(size_t)k * NMOD + n];
; #pragma unroll
;             for (int b = 0; b < 8; ++b) acc[b] += c[b * DM + k] * wv; }
; #pragma unroll
;         for (int b = 0; b < 8; ++b) red[(wid * 8 + b) * 64 + lane] = acc[b];
;         __syncthreads();
;         { const int b = wid; float s = 0.f;
; #pragma unroll
;           for (int w8 = 0; w8 < 8; ++w8) s += red[(w8 * 8 + b) * 64 + lane];
;           ((float*)(ws + WS_MOD))[b * NMOD + n] = s + a.in[4][n]; }
;         __syncthreads();
;     }
;     for (int i = bid * NTHR + tid; i < T; i += G * NTHR) { ((float*)(ws + WS_RSQ))[i] = 0.f; ((float*)(ws + WS_RSKV))[i] = 0.f; }
;     if (bid == (96 % G)) { const float* t = a.in[13]; ((float*)(ws + WS_LB))[tid] = 1.0f / (1.0f + expf(t[tid] - t[512 + tid])); }
;     LAS unsigned short* tile = (LAS unsigned short*)lds;
;     constexpr int I0 = 16 * 80, I1 = 8 * 12, I2 = 4 * 8, I2b = 4 * 8, I3 = 8 * 16, I4 = 8 * 16, I5 = 16 * 16, I6 = 16 * 88, I7 = 44 * 16;
;     constexpr int NIT = I0 + I1 + I2 + I2b + I3 + I4 + I5 + I6 + I7;
;     for (int it = bid; it < NIT; it += G) {
;         int r = it;
;         if (r < I0) { wt_item(a.in[6], 1024, 4896, (bf16_t*)(ws + WS_WIN), 1, r, 80, tile); continue; } r -= I0;
.LBB0_28:
	s_cmpk_gt_i32 s2, 0xfdf
	s_cbranch_scc1 .LBB0_121
	s_add_u32 s6, s30, 0x1f00000
	s_addc_u32 s7, s31, 0
	s_add_u32 s10, s30, 0x1400000
	s_addc_u32 s11, s31, 0
	s_add_u32 s12, s30, 0x1200000
	s_addc_u32 s13, s31, 0
	s_add_u32 s14, s30, 0x1000000
	s_addc_u32 s15, s31, 0
	s_add_u32 s16, s30, 0xf80000
	s_addc_u32 s17, s31, 0
	s_add_u32 s18, s30, 0xf00000
	s_addc_u32 s19, s31, 0
	s_add_u32 s20, s30, 0xe00000
	s_addc_u32 s21, s31, 0
	s_add_u32 s22, s30, 0x400000
	v_mul_u32_u24_e32 v0, 0x84, v18
	v_lshlrev_b32_e32 v1, 1, v152
	s_addc_u32 s23, s31, 0
	v_add3_u32 v6, 0, v0, v1
	v_lshlrev_b32_e32 v0, 3, v254
	s_waitcnt lgkmcnt(0)
	s_cmp_lg_u64 s[70:71], 0
	v_lshrrev_b32_e32 v14, 3, v254
	v_and_b32_e32 v0, 56, v0
	s_cselect_b64 s[24:25], -1, 0
	s_cmp_lg_u64 s[66:67], 0
	v_mul_u32_u24_e32 v1, 0x84, v14
	v_lshlrev_b32_e32 v2, 1, v0
	s_cselect_b64 s[26:27], -1, 0
	s_lshl_b32 s3, s2, 2
	s_mov_b32 s9, 0
	v_add_u32_e32 v7, 8, v152
	v_or_b32_e32 v8, 16, v152
	v_add_u32_e32 v9, 24, v152
	v_or_b32_e32 v10, 32, v152
	v_add_u32_e32 v11, 40, v152
	v_or_b32_e32 v12, 48, v152
	v_add_u32_e32 v13, 56, v152
	v_add3_u32 v15, 0, v1, v2
	v_mov_b32_e32 v1, 0
	v_lshlrev_b32_e32 v16, 9, v14
	s_lshl_b32 s58, s2, 6
	s_lshl_b32 s59, s86, 6
	s_add_i32 s60, s3, 0x3cb80
	s_lshl_b32 s61, s86, 2
	s_lshl_b32 s78, s2, 3
	s_lshl_b32 s79, s86, 3
	s_movk_i32 s88, 0x320
	s_movk_i32 s89, 0x4c80
	v_lshlrev_b32_e32 v2, 1, v0
	v_lshlrev_b32_e32 v17, 2, v18
	v_mov_b32_e32 v19, 0x400
	v_cndmask_b32_e64 v20, 0, 1, s[24:25]
	s_mov_b32 s90, s2
	s_cmpk_lg_i32 s86, 0x100
	s_cbranch_scc1 .Lp0_orig
	s_cmpk_lt_u32 s2, 0x60
	s_cbranch_scc1 .Lp0_stage2_init
	s_sub_i32 s90, s2, 0x60
	s_movk_i32 s98, 0xa0
	s_movk_i32 s99, 0xd20
	s_branch .Lp0_derive

; __device__ __forceinline__ void p0_phase(const Args& a, LAS unsigned char* lds, int bid, int G) {
;     ...
;     for (int it = bid; it < NIT; it += G) {
;         int r = it;
;         if (r < I0) { wt_item(a.in[6], 1024, 4896, (bf16_t*)(ws + WS_WIN), 1, r, 80, tile); continue; } r -= I0;
.Lp0_orig:
	s_mov_b32 s98, s86
	s_movk_i32 s99, 0xfe0
	s_branch .LBB0_32

; __device__ __forceinline__ void xcd_barrier(const XcdBarrier& b) {
;     asm volatile("s_waitcnt vmcnt(0)" ::: "memory");
;     __syncthreads();
;     if (threadIdx.x == 0) {
;         unsigned* bar = b.bar;
;         __builtin_amdgcn_s_waitcnt(0);
;         unsigned nloc = b.st[0], nx = b.st[1];
;         if (nloc == 0u) { xcd_barrier_complete(bar, b.x, nloc, nx); b.st[0] = nloc; b.st[1] = nx; }
.LBB0_438:
	s_cmpk_eq_i32 s86, 0x100
	s_cbranch_scc1 .LBB0_492
	s_cmp_lt_i32 s85, 5
	s_cbranch_scc1 .LBB0_492
	s_waitcnt vmcnt(0)
	s_waitcnt vmcnt(0)
	s_barrier
	s_mov_b64 s[4:5], exec
	v_readlane_b32 s6, v255, 1
	v_readlane_b32 s7, v255, 2
	s_and_b64 s[6:7], s[4:5], s[6:7]
	s_mov_b64 exec, s[6:7]
	s_cbranch_execz .LBB0_491
	s_add_i32 s3, 0, 0x23fc0
	v_mov_b32_e32 v0, s3
	s_waitcnt vmcnt(0) expcnt(0) lgkmcnt(0)
	ds_read_b32 v2, v0
	s_add_i32 s3, 0, 0x23fc4
	v_mov_b32_e32 v0, s3
	ds_read_b32 v0, v0
	s_waitcnt lgkmcnt(1)
	v_cmp_ne_u32_e32 vcc, 0, v2
	s_cbranch_vccnz .LBB0_455
	s_add_u32 s6, s30, 0x80200
	s_addc_u32 s7, s31, 0
	s_add_u32 s8, s30, 0x80400
	s_addc_u32 s9, s31, 0
	s_add_u32 s10, s30, 0x80500
	s_addc_u32 s11, s31, 0
	s_add_u32 s12, s30, 0x80600
	s_addc_u32 s13, s31, 0
	s_add_u32 s14, s30, 0x80700
	s_addc_u32 s15, s31, 0
	s_add_u32 s16, s30, 0x80800
	s_addc_u32 s17, s31, 0
	s_add_u32 s18, s30, 0x80900
	s_addc_u32 s19, s31, 0
	s_add_u32 s20, s30, 0x80a00
	s_addc_u32 s21, s31, 0
	s_add_u32 s22, s30, 0x80b00
	s_addc_u32 s23, s31, 0
	s_add_u32 s24, s30, 0x80c00
	s_addc_u32 s25, s31, 0
	s_add_u32 s26, s30, 0x80d00
	s_addc_u32 s27, s31, 0
	s_add_u32 s36, s30, 0x80e00
	s_addc_u32 s37, s31, 0
	s_add_u32 s38, s30, 0x80f00
	s_addc_u32 s39, s31, 0
	s_add_u32 s42, s30, 0x81000
	s_load_dword s3, s[0:1], 0x118
	s_addc_u32 s43, s31, 0
	s_add_u32 s48, s30, 0x81100
	s_addc_u32 s49, s31, 0
	s_add_u32 s54, s30, 0x81200
	s_addc_u32 s55, s31, 0
	s_waitcnt lgkmcnt(0)
	s_mul_i32 s3, s87, s3
	s_add_u32 s58, s30, 0x81300
	s_mul_i32 s3, s3, s86
	s_addc_u32 s59, s31, 0
	s_mov_b32 s28, 1
	v_mov_b32_e32 v16, 0
	s_branch .LBB0_443

;     __host__ __device__ void init(int M, int N, int G_, int c_) { base.init(M, N, G_, c_); }
; __device__ __forceinline__ unsigned cvt_pk_bf16(float lo, float hi) { unsigned r; asm volatile("v_cvt_pk_bf16_f32 %0, %1, %2" : "=v"(r) : "v"(lo), "v"(hi)); return r; }
;     __device__ __forceinline__ void operator()(const f32x4 (&acc)[2][2][4][2], const Unit& u, int wr, int wc, int fr, int fq) const {
;     ...
;                 for (int m = 0; m < 4; ++m) { const f32x4 v0 = acc[ai][bj][m][0] * s0, v1 = acc[ai][bj][m][1] * s1;
;                     u32x4 w; w.x = cvt_pk_bf16(v0[0], v0[1]); w.y = cvt_pk_bf16(v0[2], v0[3]); w.z = cvt_pk_bf16(v1[0], v1[1]); w.w = cvt_pk_bf16(v1[2], v1[3]);
;                     *(u32x4*)(O + (size_t)(row0 + ai * HALF + m * 16) * ldc + col0 + bj * HALF) = w; }
; __global__ void __launch_bounds__(NTHR) mk_fwd(Args a) {
;     ...
;                { pg8::Gemm g{WSB(WS_WUKV + 512 * 1024), WSB(SL(5)), 512, T, 256, 512}; pg8::StaticOrder S; S.init(512, T, G, bid);
;                  pg8::EpiColScale E{WSB(SL(8)), T, (const float*)(ws + WS_RSKV), 1.f / 256.f};
;                  pg8::gemm_phase<pg8::EpiColScale, pg8::StaticOrder, true, true>(lds, g, S, E); } )
.LBB0_551:
	s_cmpk_lg_i32 s86, 0x100
	s_cbranch_scc1 .Lvt_pd
	s_cmp_eq_u32 s6, 0
	s_cbranch_scc0 .Lvt_p1
	s_add_u32 s24, s50, 0x7000000
	s_addc_u32 s25, s51, 0
	s_branch .Lvt_pd

; #define PHASE(k, ...) if (IN(k)) { { __VA_ARGS__ } if (DUPON(k)) { __VA_ARGS__ } SEAM(k); }
; __global__ void __launch_bounds__(NTHR) mk_fwd(Args a) {
;     ...
;     PHASE(7,  const bf16_t* Q = WSB(SL(3)); const bf16_t* K = (const bf16_t*)((unsigned char*)a.out + 64 * MiB); const bf16_t* Vt = WSB(SL(8)); bf16_t* O = (bf16_t*)a.out;
;                  float mfix; { const int ln = threadIdx.x & 63; float gqm = fmaxf(fabsf(a.in[11][ln]), fabsf(a.in[11][64 + (ln & 31)])), gkm = fmaxf(fabsf(a.in[12][ln]), fabsf(a.in[12][64 + (ln & 31)]));
;                      for (int o = 1; o < 64; o <<= 1) { gqm = fmaxf(gqm, __shfl_xor(gqm, o)); gkm = fmaxf(gkm, __shfl_xor(gkm, o)); }
;                      mfix = 14.135f * 1.02f * gqm * gkm; }
;                  const bool fix = mfix <= 40.f;
;                  for (int rep = 0; rep < (DUPON(19) ? 2 : 1); ++rep) {
;                  if (fix) { if (G == 256) { const int bh = bid >> 2, s = bid & 3; attn_unit64(Q, K, Vt, O, bh, 7 - s, mfix, lds); attn_unit64(Q, K, Vt, O, bh, s, mfix, lds); }
.LBB0_704:
	s_cmp_lt_i32 s84, 8
	s_cselect_b64 s[0:1], -1, 0
	s_cmp_gt_i32 s85, 7
	s_cselect_b64 s[4:5], -1, 0
	s_and_b64 s[0:1], s[0:1], s[4:5]
	s_andn2_b64 vcc, exec, s[0:1]
	s_cbranch_vccnz .LBB0_893
	s_mov_b32 s98, 0
	s_cmpk_lg_i32 s86, 0x100
	s_cbranch_scc1 .Lp7_setup
	s_and_b32 s99, s2, 8
	s_cbranch_scc0 .Lp7_setup
	s_mov_b32 s98, 1
	v_writelane_b32 v255, s74, 9
	v_writelane_b32 v255, s75, 10
	v_writelane_b32 v255, s76, 11
	v_writelane_b32 v255, s77, 12
.Lp7_setup:
	v_and_b32_e32 v195, 31, v254
	s_waitcnt vmcnt(0)
	v_and_b32_e32 v0, 63, v254
	s_waitcnt lgkmcnt(0)
	v_lshlrev_b32_e32 v1, 2, v195
	v_lshlrev_b32_e32 v0, 2, v0
	global_load_dword v2, v1, s[74:75] offset:256
	global_load_dword v3, v0, s[74:75]
	global_load_dword v4, v1, s[76:77] offset:256
	global_load_dword v5, v0, s[76:77]
	v_mbcnt_lo_u32_b32 v0, -1, 0
	v_lshlrev_b32_e32 v16, 3, v254
	v_mbcnt_hi_u32_b32 v0, -1, v0
	v_and_b32_e32 v10, 56, v16
	v_and_b32_e32 v201, 64, v0
	v_add_u32_e32 v6, 0x200, v254
	v_xor_b32_e32 v17, 1, v0
	v_lshlrev_b32_e32 v158, 1, v10
	v_add_u32_e32 v10, 64, v201
	v_mul_u32_u24_e32 v8, 0x1556, v254
	v_mov_b32_e32 v9, 12
	s_mov_b32 s4, 0x7060302
	v_mul_u32_u24_e32 v12, 0x1556, v6
	v_cmp_lt_i32_e32 vcc, v17, v10
	v_mul_lo_u16_sdwa v11, v8, v9 dst_sel:DWORD dst_unused:UNUSED_PAD src0_sel:WORD_1 src1_sel:DWORD
	v_perm_b32 v8, v12, v8, s4
	v_mul_lo_u16_sdwa v9, v12, v9 dst_sel:DWORD dst_unused:UNUSED_PAD src0_sel:WORD_1 src1_sel:DWORD
	v_cndmask_b32_e32 v12, v0, v17, vcc
	v_lshlrev_b32_e32 v12, 2, v12
	v_lshrrev_b32_e32 v7, 3, v254
	v_xor_b32_e32 v18, 2, v0
	v_bfe_u32 v1, v254, 5, 1
	s_movk_i32 s6, 0xd0
	v_mul_u32_u24_e32 v13, 0x88, v7
	v_xor_b32_e32 v19, 4, v0
	v_cmp_lt_i32_e32 vcc, v18, v10
	v_lshlrev_b32_e32 v199, 3, v1
	v_mad_u32_u24 v14, v195, s6, 0
	v_lshlrev_b32_e32 v156, 4, v1
	v_mul_i32_i24_e32 v15, 0xffffffb8, v195
	v_xor_b32_e32 v20, 8, v0
	v_add3_u32 v189, 0, v13, v158
	v_cndmask_b32_e32 v13, v0, v18, vcc
	v_cmp_lt_i32_e32 vcc, v19, v10
	v_xor_b32_e32 v21, 16, v0
	v_add_u32_e32 v188, v14, v156
	v_add3_u32 v198, v14, v15, v199
	v_cndmask_b32_e32 v14, v0, v19, vcc
	v_cmp_lt_i32_e32 vcc, v20, v10
	v_xor_b32_e32 v22, 32, v0
	v_sub_u16_e32 v9, v6, v9
	v_cndmask_b32_e32 v15, v0, v20, vcc
	v_cmp_lt_i32_e32 vcc, v21, v10
	v_lshlrev_b32_e32 v190, 4, v9
	v_lshlrev_b32_e32 v9, 2, v15
	v_cndmask_b32_e32 v17, v0, v21, vcc
	v_cmp_lt_i32_e32 vcc, v22, v10
	v_lshlrev_b32_e32 v10, 2, v13
	v_lshlrev_b32_e32 v186, 2, v17
	v_cndmask_b32_e32 v0, v0, v22, vcc
	v_lshlrev_b32_e32 v187, 2, v0
	s_add_u32 s49, s50, 0x4000000
	s_addc_u32 s54, s51, 0
	s_add_u32 s55, s30, 0x6000000
	s_addc_u32 s56, s31, 0
	s_add_u32 s59, s30, 0x10000000
	s_addc_u32 s60, s31, 0
	s_cmpk_lg_i32 s86, 0x100
	s_cbranch_scc1 .Lvt_cd
	s_bitcmp1_b32 s2, 4
	s_cbranch_scc1 .Lvt_c1
	s_add_u32 s59, s50, 0x7000000
	s_addc_u32 s60, s51, 0
	s_branch .Lvt_cd
